# P0 WQ/W_in-u elementwise conversion loops: unrolled fast path issuing all iterations' loads up-front (4 resp. 2 serialized round trips -> 1)
# speedup vs baseline: 1.0136x; 1.0136x over previous
; __device__ __forceinline__ unsigned cvt_pk_bf16(float lo, float hi) { const f32x2 v = {lo, hi}; const bf16x2_t r = __builtin_convertvector(v, bf16x2_t); return __builtin_bit_cast(unsigned, r); }
; __global__ void __launch_bounds__(NTHR, 2) fwd_megakernel(Params p) {
;     ...
;         for (size_t i = gtid; i < (size_t)D * D / 8; i += NGT) { const f32x4 a = ((const f32x4*)p.wq)[2 * i], b = ((const f32x4*)p.wq)[2 * i + 1];
;             u32x4 w; w.x = cvt_pk_bf16(a[0], a[1]); w.y = cvt_pk_bf16(a[2], a[3]); w.z = cvt_pk_bf16(b[0], b[1]); w.w = cvt_pk_bf16(b[2], b[3]); ((u32x4*)WQ)[i] = w; }
.LBB0_60:
	s_ashr_i32 s3, s2, 31
	s_lshl_b64 s[0:1], s[2:3], 9
	v_lshl_add_u64 v[0:1], s[0:1], 0, v[184:185]
	s_mov_b64 s[6:7], 0x80000
	s_lshl_b64 s[4:5], s[34:35], 9
	v_cmp_gt_u64_e32 vcc, s[6:7], v[0:1]
	v_lshlrev_b32_e32 v192, 4, v184
	s_and_saveexec_b64 s[6:7], vcc
	s_cbranch_execz .LBB0_63
	s_lshl_b64 s[10:11], s[2:3], 13
	s_add_u32 s10, s26, s10
	v_mov_b32_e32 v193, 0
	s_addc_u32 s11, s27, s11
	v_lshl_add_u64 v[2:3], s[10:11], 0, v[192:193]
	s_mov_b64 s[10:11], 0xac14000
	v_lshl_add_u64 v[2:3], v[2:3], 0, s[10:11]
	s_lshl_b64 s[10:11], s[34:35], 13
	s_lshl_b64 s[12:13], s[2:3], 14
	v_readlane_b32 s36, v251, 37
	v_readlane_b32 s37, v251, 38
	s_add_u32 s12, s36, s12
	v_lshlrev_b32_e32 v4, 5, v184
	v_mov_b32_e32 v5, v193
	s_addc_u32 s13, s37, s13
	v_readlane_b32 s38, v251, 39
	v_readlane_b32 s39, v251, 40
	v_lshl_add_u64 v[4:5], s[12:13], 0, v[4:5]
	v_lshl_add_u64 v[4:5], v[4:5], 0, 16
	s_lshl_b64 s[12:13], s[34:35], 14
	s_mov_b64 s[36:37], 0
	s_mov_b64 s[38:39], 0x7ffff
	v_mov_b64_e32 v[6:7], v[0:1]
	v_readlane_b32 s40, v251, 41
	v_readlane_b32 s41, v251, 42
	v_readlane_b32 s42, v251, 43
	v_readlane_b32 s43, v251, 44
	v_readlane_b32 s44, v251, 45
	v_readlane_b32 s45, v251, 46
	v_readlane_b32 s46, v251, 47
	v_readlane_b32 s47, v251, 48
	v_readlane_b32 s48, v251, 49
	v_readlane_b32 s49, v251, 50
	v_readlane_b32 s50, v251, 51
	v_readlane_b32 s51, v251, 52
	s_cmp_eq_u32 s4, 0x20000
	s_cbranch_scc0 .LBB0_62
	s_cmp_eq_u32 s5, 0
	s_cbranch_scc0 .LBB0_62
	v_lshl_add_u64 v[40:41], v[4:5], 0, s[12:13]
	v_lshl_add_u64 v[42:43], v[40:41], 0, s[12:13]
	v_lshl_add_u64 v[44:45], v[42:43], 0, s[12:13]
	global_load_dwordx4 v[8:11], v[4:5], off offset:-16
	global_load_dwordx4 v[12:15], v[4:5], off
	global_load_dwordx4 v[16:19], v[40:41], off offset:-16
	global_load_dwordx4 v[20:23], v[40:41], off
	global_load_dwordx4 v[24:27], v[42:43], off offset:-16
	global_load_dwordx4 v[28:31], v[42:43], off
	global_load_dwordx4 v[32:35], v[44:45], off offset:-16
	global_load_dwordx4 v[36:39], v[44:45], off
	v_lshl_add_u64 v[40:41], v[2:3], 0, s[10:11]
	v_lshl_add_u64 v[42:43], v[40:41], 0, s[10:11]
	v_lshl_add_u64 v[44:45], v[42:43], 0, s[10:11]
	s_waitcnt vmcnt(6)
	v_cvt_pk_bf16_f32 v8, v8, v9
	v_cvt_pk_bf16_f32 v9, v10, v11
	v_cvt_pk_bf16_f32 v10, v12, v13
	v_cvt_pk_bf16_f32 v11, v14, v15
	global_store_dwordx4 v[2:3], v[8:11], off
	s_waitcnt vmcnt(5)
	v_cvt_pk_bf16_f32 v16, v16, v17
	v_cvt_pk_bf16_f32 v17, v18, v19
	v_cvt_pk_bf16_f32 v18, v20, v21
	v_cvt_pk_bf16_f32 v19, v22, v23
	global_store_dwordx4 v[40:41], v[16:19], off
	s_waitcnt vmcnt(4)
	v_cvt_pk_bf16_f32 v24, v24, v25
	v_cvt_pk_bf16_f32 v25, v26, v27
	v_cvt_pk_bf16_f32 v26, v28, v29
	v_cvt_pk_bf16_f32 v27, v30, v31
	global_store_dwordx4 v[42:43], v[24:27], off
	s_waitcnt vmcnt(3)
	v_cvt_pk_bf16_f32 v32, v32, v33
	v_cvt_pk_bf16_f32 v33, v34, v35
	v_cvt_pk_bf16_f32 v34, v36, v37
	v_cvt_pk_bf16_f32 v35, v38, v39
	global_store_dwordx4 v[44:45], v[32:35], off
	s_branch .LBB0_63

; __device__ __forceinline__ unsigned cvt_pk_bf16(float lo, float hi) { const f32x2 v = {lo, hi}; const bf16x2_t r = __builtin_convertvector(v, bf16x2_t); return __builtin_bit_cast(unsigned, r); }
; __global__ void __launch_bounds__(NTHR, 2) fwd_megakernel(Params p) {
;     ...
;         for (size_t i = gtid; i < (size_t)D * 1024 / 8; i += NGT) { const size_t kd = i >> 7, c = (i & 127) * 8; const float* src = p.w_in + kd * 4112 + c;
;             const f32x4 a = *(const f32x4*)src, b = *(const f32x4*)(src + 4);
;             u32x4 w; w.x = cvt_pk_bf16(a[0], a[1]); w.y = cvt_pk_bf16(a[2], a[3]); w.z = cvt_pk_bf16(b[0], b[1]); w.w = cvt_pk_bf16(b[2], b[3]); ((u32x4*)MIX)[i] = w; }
.LBB0_63:
	s_or_b64 exec, exec, s[6:7]
	s_mov_b64 s[6:7], 0x40000
	v_cmp_gt_u64_e32 vcc, s[6:7], v[0:1]
	s_and_saveexec_b64 s[6:7], vcc
	s_cbranch_execz .LBB0_66
	v_mov_b32_e32 v3, 0
	s_lshl_b64 s[10:11], s[2:3], 12
	v_mov_b32_e32 v191, v3
	v_lshl_add_u64 v[4:5], s[10:11], 0, v[190:191]
	s_lshl_b64 s[10:11], s[34:35], 12
	s_lshl_b64 s[12:13], s[2:3], 13
	s_add_u32 s12, s26, s12
	v_mov_b32_e32 v193, v3
	s_addc_u32 s13, s27, s13
	v_readlane_b32 s40, v251, 1
	v_lshl_add_u64 v[6:7], s[12:13], 0, v[192:193]
	s_mov_b64 s[12:13], 0x1bc14000
	v_readlane_b32 s54, v251, 15
	v_readlane_b32 s55, v251, 16
	v_lshl_add_u64 v[6:7], v[6:7], 0, s[12:13]
	s_lshl_b64 s[12:13], s[34:35], 13
	s_mov_b64 s[36:37], 0
	s_movk_i32 s18, 0x4040
	v_mov_b64_e32 v[8:9], s[54:55]
	s_mov_b64 s[38:39], 0x3ffff
	v_mov_b64_e32 v[10:11], v[0:1]
	v_readlane_b32 s41, v251, 2
	v_readlane_b32 s42, v251, 3
	v_readlane_b32 s43, v251, 4
	v_readlane_b32 s44, v251, 5
	v_readlane_b32 s45, v251, 6
	v_readlane_b32 s46, v251, 7
	v_readlane_b32 s47, v251, 8
	v_readlane_b32 s48, v251, 9
	v_readlane_b32 s49, v251, 10
	v_readlane_b32 s50, v251, 11
	v_readlane_b32 s51, v251, 12
	v_readlane_b32 s52, v251, 13
	v_readlane_b32 s53, v251, 14
	s_cmp_eq_u32 s4, 0x20000
	s_cbranch_scc0 .LBB0_65
	s_cmp_eq_u32 s5, 0
	s_cbranch_scc0 .LBB0_65
	v_lshrrev_b32_e32 v2, 7, v10
	v_and_b32_e32 v14, 0x3f8, v4
	v_mad_u64_u32 v[12:13], s[20:21], v2, s18, v[8:9]
	v_lshlrev_b32_e32 v2, 2, v14
	v_lshl_add_u64 v[16:17], v[12:13], 0, v[2:3]
	s_mov_b32 s36, 0x1010000
	s_mov_b32 s37, 0
	v_lshl_add_u64 v[20:21], v[16:17], 0, s[36:37]
	global_load_dwordx4 v[24:27], v[16:17], off
	global_load_dwordx4 v[28:31], v[16:17], off offset:16
	global_load_dwordx4 v[32:35], v[20:21], off
	global_load_dwordx4 v[36:39], v[20:21], off offset:16
	v_lshl_add_u64 v[20:21], v[6:7], 0, s[12:13]
	s_waitcnt vmcnt(2)
	v_cvt_pk_bf16_f32 v24, v24, v25
	v_cvt_pk_bf16_f32 v25, v26, v27
	v_cvt_pk_bf16_f32 v26, v28, v29
	v_cvt_pk_bf16_f32 v27, v30, v31
	global_store_dwordx4 v[6:7], v[24:27], off
	s_waitcnt vmcnt(1)
	v_cvt_pk_bf16_f32 v32, v32, v33
	v_cvt_pk_bf16_f32 v33, v34, v35
	v_cvt_pk_bf16_f32 v34, v36, v37
	v_cvt_pk_bf16_f32 v35, v38, v39
	global_store_dwordx4 v[20:21], v[32:35], off
	s_branch .LBB0_66
